# phase U: half of the workgroups (bit 3 of index) run their X and S5 units before their A units, de-synchronising LDS-DMA-bound GEMMs from VALU/latency-bound units inside every XCD
# speedup vs baseline: 1.1224x; 1.0138x over previous
; template <int N> DI void wait_vm() { asm volatile("s_waitcnt vmcnt(%0)" ::"n"(N) : "memory"); }
; DI void fast_grid_barrier(unsigned* ctr, unsigned target) {
;     wait_vm<0>();
;     __syncthreads();
;     if (threadIdx.x == 0) {
;         __builtin_amdgcn_fence(__ATOMIC_RELEASE, "agent");
;         __hip_atomic_fetch_add(ctr, 1u, __ATOMIC_RELAXED, __HIP_MEMORY_SCOPE_AGENT);
;         while (__hip_atomic_load(ctr, __ATOMIC_RELAXED, __HIP_MEMORY_SCOPE_AGENT) < target) __builtin_amdgcn_s_sleep(6);
;         __builtin_amdgcn_fence(__ATOMIC_ACQUIRE, "agent");
;     }
;     __syncthreads();
; }
.Lcen_xb_loop:
	v_mov_b32_e32 v23, 0x280
	v_add_u32_e32 v24, 0x280, v2
	global_load_dword v4, v23, s[10:11] offset:0 sc1
	global_load_dword v5, v23, s[10:11] offset:4 sc1
	global_load_dword v6, v23, s[10:11] offset:8 sc1
	global_load_dword v7, v23, s[10:11] offset:12 sc1
	global_load_dword v8, v23, s[10:11] offset:16 sc1
	global_load_dword v9, v23, s[10:11] offset:20 sc1
	global_load_dword v10, v23, s[10:11] offset:24 sc1
	global_load_dword v11, v23, s[10:11] offset:28 sc1
	global_load_dword v12, v23, s[10:11] offset:32 sc1
	global_load_dword v13, v23, s[10:11] offset:36 sc1
	global_load_dword v14, v23, s[10:11] offset:40 sc1
	global_load_dword v15, v23, s[10:11] offset:44 sc1
	global_load_dword v16, v23, s[10:11] offset:48 sc1
	global_load_dword v17, v23, s[10:11] offset:52 sc1
	global_load_dword v18, v23, s[10:11] offset:56 sc1
	global_load_dword v19, v23, s[10:11] offset:60 sc1
	global_load_dword v20, v24, s[10:11] sc1
	s_waitcnt vmcnt(0)
	v_add3_u32 v21, v4, v5, v6
	v_add3_u32 v21, v21, v7, v8
	v_add3_u32 v21, v21, v9, v10
	v_add3_u32 v21, v21, v11, v12
	v_add3_u32 v21, v21, v13, v14
	v_add3_u32 v21, v21, v15, v16
	v_add3_u32 v21, v21, v17, v18
	v_add_u32_e32 v21, v21, v19
	v_cmp_ne_u32_e32 vcc, s2, v21
	s_cbranch_vccz .Lcen_xb_ok
	s_sleep 2
	s_branch .Lcen_xb_loop

; template <int N> DI void wait_vm() { asm volatile("s_waitcnt vmcnt(%0)" ::"n"(N) : "memory"); }
; DI void fast_grid_barrier(unsigned* ctr, unsigned target) {
;     wait_vm<0>();
;     __syncthreads();
;     if (threadIdx.x == 0) {
;         __builtin_amdgcn_fence(__ATOMIC_RELEASE, "agent");
;         __hip_atomic_fetch_add(ctr, 1u, __ATOMIC_RELAXED, __HIP_MEMORY_SCOPE_AGENT);
;         while (__hip_atomic_load(ctr, __ATOMIC_RELAXED, __HIP_MEMORY_SCOPE_AGENT) < target) __builtin_amdgcn_s_sleep(6);
;         __builtin_amdgcn_fence(__ATOMIC_ACQUIRE, "agent");
;     }
;     __syncthreads();
; }
.Lcen_xb_done:
	v_add_u32_e32 v23, 0x2c0, v2
	v_add_u32_e32 v24, 0x300, v2
	v_mov_b32_e32 v25, 0x340
	v_mov_b32_e32 v26, 0x344
	global_atomic_add v0, v23, v3, s[10:11] sc0
	s_waitcnt vmcnt(0)
	v_readfirstlane_b32 s6, v0
	s_nop 3
	s_add_u32 s6, s6, 1
	s_mul_i32 s7, s12, s3
	s_cmp_eq_u32 s6, s7
	s_cbranch_scc0 .Lxb_follow
	buffer_wbl2 sc1
	s_waitcnt vmcnt(0)
	global_atomic_add v0, v25, v3, s[10:11] sc0
	s_waitcnt vmcnt(0)
	v_readfirstlane_b32 s6, v0
	v_readlane_b32 s7, v245, 1
	s_nop 3
	s_add_u32 s6, s6, 1
	s_mul_i32 s7, s12, s7
	s_cmp_eq_u32 s6, s7
	s_cbranch_scc0 .Lxb_wait_top
	global_atomic_add v26, v3, s[10:11]
	s_branch .Lxb_top_done
.Lxb_wait_top:
	s_sleep 1
	global_load_dword v0, v26, s[10:11] sc1
	s_waitcnt vmcnt(0)
	v_cmp_gt_u32_e32 vcc, s12, v0
	s_cbranch_vccnz .Lxb_wait_top
.Lxb_top_done:
	buffer_inv sc1
	global_atomic_add v24, v3, s[10:11]
	s_waitcnt vmcnt(0)
	s_branch .LBB0_69
.Lxb_follow:
	s_sleep 1
	global_load_dword v0, v24, s[10:11] sc1
	s_waitcnt vmcnt(0)
	v_cmp_gt_u32_e32 vcc, s12, v0
	s_cbranch_vccnz .Lxb_follow
	buffer_inv sc1
	s_waitcnt vmcnt(0)

; template <int N> DI void wait_vm() { asm volatile("s_waitcnt vmcnt(%0)" ::"n"(N) : "memory"); }
; DI void signal_done(unsigned* c) {
;     wait_vm<0>();
;     __syncthreads();
;     if (threadIdx.x == 0) { __builtin_amdgcn_fence(__ATOMIC_RELEASE, "agent"); __hip_atomic_fetch_add(c, 1u, __ATOMIC_RELAXED, __HIP_MEMORY_SCOPE_AGENT); }
; }
.LBB0_81:
	s_or_b64 exec, exec, s[0:1]
	s_barrier
	s_mov_b64 s[0:1], exec
	v_readlane_b32 s2, v243, 32
	v_readlane_b32 s3, v243, 33
	s_nop 3
	s_and_b64 s[2:3], s[0:1], s[2:3]
	s_mov_b64 exec, s[2:3]
	s_cbranch_execz .Lxb_posted
	v_readlane_b32 s10, v244, 42
	v_readlane_b32 s11, v244, 43
	s_getreg_b32 s6, hwreg(HW_REG_XCC_ID, 0, 4)
	s_lshl_b32 s6, s6, 2
	v_mov_b32_e32 v2, s6
	v_add_u32_e32 v2, 0x280, v2
	v_mov_b32_e32 v3, 1
	s_nop 4
	global_atomic_add v2, v3, s[10:11]

; __global__ void __launch_bounds__(NTHR) mega_fwd(Params p) {
;     ...
;     for (int ph = 0; ph < 4; ++ph) {
;         if (ph == 0) grid.sync(); else fast_grid_barrier(bar, (unsigned)ph * (unsigned)nb);
;         const int l = ph >> 1;
;         if ((ph & 1) == 0) {
;             const int nkv = (l == 0) ? 256 : 0, nunits = 256 + nkv + 1024 + 256 + 256;
;             for (int u = bid; u < nunits; u += nb) {
;                 int v = u;
;                 if (v < 256) { unit_B1(p, lds, l, v); continue; }
;                 v -= 256;
;                 if (v < nkv) { unit_KV(p, lds, v >> 7, (v >> 2) & 31, v & 3); continue; }
;                 v -= nkv;
;                 if (v < 1024) { unit_A(p, lds, l, v & 255, v >> 8); continue; }
;                 v -= 1024;
;                 const int s = v & 255, xcd = s & 7, i = s >> 3;
;                 if (v < 256) unit_X(p, lds, l, xcd * 32 + i);
;                 else unit_S5(p, lds, l, xcd * 2 + (i >> 4), i & 15);
;             }
.LBB0_662:
	v_readlane_b32 s2, v245, 5
	s_nop 3
	v_readlane_b32 s0, v244, 18
	s_add_i32 s2, s2, s0
	s_add_i32 s72, s72, s0
	s_cmp_ge_i32 s2, s25
	v_readlane_b32 s1, v244, 19
	s_cbranch_scc1 .LBB0_60
.LBB0_663:
	v_writelane_b32 v245, s2, 5
	s_bitcmp1_b32 s2, 3
	s_cbranch_scc0 .Lperm_done
	s_lshr_b32 s0, s2, 8
	s_lshl_b32 s0, s0, 2
	s_mov_b32 s1, 0x54327610
	s_mov_b32 s3, 0x04321650
	s_cmp_lg_u32 s24, 0
	s_cselect_b32 s1, s1, s3
	s_lshr_b32 s1, s1, s0
	s_and_b32 s1, s1, 15
	s_and_b32 s2, s2, 0xff
	s_lshl_b32 s1, s1, 8
	s_or_b32 s2, s2, s1

; DI void wait_count(unsigned* c, unsigned need) {
;     if (threadIdx.x == 0) {
;         while (__hip_atomic_load(c, __ATOMIC_RELAXED, __HIP_MEMORY_SCOPE_AGENT) < need) __builtin_amdgcn_s_sleep(1);
;         __builtin_amdgcn_fence(__ATOMIC_ACQUIRE, "agent");
;     }
;     __syncthreads();
; }
.Lxs_s5_wait:
	v_mov_b32_e32 v51, 0x348
	global_load_dword v51, v51, s[10:11] sc1
	s_waitcnt vmcnt(0)
	v_cmp_gt_u32_e32 vcc, s8, v51
	s_cbranch_vccz .Lxs_s5_ok
	s_sleep 1
	s_branch .Lxs_s5_wait

; DI void wait_count(unsigned* c, unsigned need) {
;     if (threadIdx.x == 0) {
;         while (__hip_atomic_load(c, __ATOMIC_RELAXED, __HIP_MEMORY_SCOPE_AGENT) < need) __builtin_amdgcn_s_sleep(1);
;         __builtin_amdgcn_fence(__ATOMIC_ACQUIRE, "agent");
;     }
;     __syncthreads();
; }
.Lxs_x_wait:
	v_mov_b32_e32 v0, 0x34c
	global_load_dword v0, v0, s[8:9] sc1
	s_waitcnt vmcnt(0)
	v_cmp_gt_u32_e32 vcc, s1, v0
	s_cbranch_vccz .Lxs_x_ok
	s_sleep 1
	s_branch .Lxs_x_wait

; DI void wait_count(unsigned* c, unsigned need) {
;     if (threadIdx.x == 0) {
;         while (__hip_atomic_load(c, __ATOMIC_RELAXED, __HIP_MEMORY_SCOPE_AGENT) < need) __builtin_amdgcn_s_sleep(1);
;         __builtin_amdgcn_fence(__ATOMIC_ACQUIRE, "agent");
;     }
;     __syncthreads();
; }
.Lcen_kv_loop:
	v_mov_b32_e32 v23, 0x280
	v_add_u32_e32 v24, 0x280, v2
	global_load_dword v4, v23, s[10:11] offset:0 sc1
	global_load_dword v5, v23, s[10:11] offset:4 sc1
	global_load_dword v6, v23, s[10:11] offset:8 sc1
	global_load_dword v7, v23, s[10:11] offset:12 sc1
	global_load_dword v8, v23, s[10:11] offset:16 sc1
	global_load_dword v9, v23, s[10:11] offset:20 sc1
	global_load_dword v10, v23, s[10:11] offset:24 sc1
	global_load_dword v11, v23, s[10:11] offset:28 sc1
	global_load_dword v12, v23, s[10:11] offset:32 sc1
	global_load_dword v13, v23, s[10:11] offset:36 sc1
	global_load_dword v14, v23, s[10:11] offset:40 sc1
	global_load_dword v15, v23, s[10:11] offset:44 sc1
	global_load_dword v16, v23, s[10:11] offset:48 sc1
	global_load_dword v17, v23, s[10:11] offset:52 sc1
	global_load_dword v18, v23, s[10:11] offset:56 sc1
	global_load_dword v19, v23, s[10:11] offset:60 sc1
	global_load_dword v20, v24, s[10:11] sc1
	s_waitcnt vmcnt(0)
	v_add3_u32 v21, v4, v5, v6
	v_add3_u32 v21, v21, v7, v8
	v_add3_u32 v21, v21, v9, v10
	v_add3_u32 v21, v21, v11, v12
	v_add3_u32 v21, v21, v13, v14
	v_add3_u32 v21, v21, v15, v16
	v_add3_u32 v21, v21, v17, v18
	v_add_u32_e32 v21, v21, v19
	v_cmp_ne_u32_e32 vcc, s0, v21
	s_cbranch_vccz .Lcen_kv_ok
	s_sleep 2
	s_branch .Lcen_kv_loop

; template <int N> DI void wait_vm() { asm volatile("s_waitcnt vmcnt(%0)" ::"n"(N) : "memory"); }
; DI void signal_done(unsigned* c) {
;     wait_vm<0>();
;     __syncthreads();
;     if (threadIdx.x == 0) { __builtin_amdgcn_fence(__ATOMIC_RELEASE, "agent"); __hip_atomic_fetch_add(c, 1u, __ATOMIC_RELAXED, __HIP_MEMORY_SCOPE_AGENT); }
; }
; DI void unit_KV(const Params& p, char* lds, int l, int mtile, int q) {
;     ...
;     signal_done(WS_PTR(unsigned, OFF_HL) + 64 + l * 16 + (mtile >> 1));
.Lcen_kv_done:
	v_add_u32_e32 v23, 0x1c0, v2
	v_mov_b32_e32 v24, 0x34c
	global_atomic_add v0, v23, v3, s[10:11] sc0
	s_waitcnt vmcnt(0)
	v_readfirstlane_b32 s9, v0
	s_nop 3
	s_add_u32 s9, s9, 1
	s_cmp_eq_u32 s9, s8
	s_cbranch_scc0 .LBB0_890
	buffer_wbl2 sc1
	s_waitcnt vmcnt(0)
	global_atomic_add v24, v3, s[10:11]

; template <int N> DI void wait_vm() { asm volatile("s_waitcnt vmcnt(%0)" ::"n"(N) : "memory"); }
; DI void signal_done(unsigned* c) {
;     wait_vm<0>();
;     __syncthreads();
;     if (threadIdx.x == 0) { __builtin_amdgcn_fence(__ATOMIC_RELEASE, "agent"); __hip_atomic_fetch_add(c, 1u, __ATOMIC_RELAXED, __HIP_MEMORY_SCOPE_AGENT); }
; }
; DI void unit_B1(const Params& p, char* lds, int l, int chunk) {
;     ...
;     signal_done(WS_PTR(unsigned, OFF_HL) + 128 + l * 16 + (chunk >> 4));
.Lcen_b1_done:
	v_readlane_b32 s1, v243, 38
	s_nop 3
	s_lshr_b32 s1, s1, 1
	s_add_u32 s1, s1, 1
	v_add_u32_e32 v23, 0x180, v2
	v_mov_b32_e32 v24, 0x348
	global_atomic_add v0, v23, v3, s[10:11] sc0
	s_waitcnt vmcnt(0)
	v_readfirstlane_b32 s6, v0
	s_nop 3
	s_add_u32 s6, s6, 1
	s_mul_i32 s7, s1, s3
	s_cmp_eq_u32 s6, s7
	s_cbranch_scc0 .LBB0_661
	buffer_wbl2 sc1
	s_waitcnt vmcnt(0)
	global_atomic_add v24, v3, s[10:11]
	s_branch .LBB0_661
